# mLSTM walk: the per-step normaliser element is read from LDS at the start of the compute segment instead of in the serial tail before the step barrier
# baseline (speedup 1.0000x reference)
.LBB0_541:
	s_or_b64 exec, exec, s[10:11]
	s_waitcnt lgkmcnt(0)
	s_barrier
	ds_read_b32 v233, v131 offset:46336
	ds_read_b96 v[54:56], v71 offset:46720
	s_and_b64 vcc, exec, s[60:61]
	s_mov_b64 s[10:11], -1
	s_cbranch_vccnz .LBB0_545
	ds_read_b128 v[46:49], v168
	ds_read_b128 v[50:53], v168 offset:16
	ds_read_b128 v[198:201], v168 offset:32
	ds_read_b128 v[202:205], v183 offset:46336
	ds_read_b128 v[234:237], v183 offset:46352
	ds_read_b128 v[238:241], v183 offset:46368
	ds_read_b128 v[242:245], v183 offset:46384
	s_waitcnt lgkmcnt(6)
	v_lshlrev_b32_e32 v93, 16, v46
	v_and_b32_e32 v46, 0xffff0000, v46
	s_waitcnt lgkmcnt(3)
	v_mul_f32_e32 v46, v203, v46
	v_fmac_f32_e32 v46, v202, v93
	v_lshlrev_b32_e32 v93, 16, v47
	v_fmac_f32_e32 v46, v204, v93
	v_and_b32_e32 v47, 0xffff0000, v47
	v_fmac_f32_e32 v46, v205, v47
	v_lshlrev_b32_e32 v47, 16, v48
	s_waitcnt lgkmcnt(2)
	v_fmac_f32_e32 v46, v234, v47
	v_and_b32_e32 v47, 0xffff0000, v48
	v_fmac_f32_e32 v46, v235, v47
	v_lshlrev_b32_e32 v47, 16, v49
	v_fmac_f32_e32 v46, v236, v47
	v_and_b32_e32 v47, 0xffff0000, v49
	v_fmac_f32_e32 v46, v237, v47
	v_and_b32_e32 v47, 0xffff0000, v50
	v_add_f32_e32 v93, 0, v46
	v_lshlrev_b32_e32 v46, 16, v50
	s_waitcnt lgkmcnt(1)
	v_mul_f32_e32 v50, v239, v47
	v_fmac_f32_e32 v50, v238, v46
	v_lshlrev_b32_e32 v46, 16, v51
	v_fmac_f32_e32 v50, v240, v46
	v_and_b32_e32 v46, 0xffff0000, v51
	v_fmac_f32_e32 v50, v241, v46
	v_lshlrev_b32_e32 v51, 16, v52
	ds_read_b128 v[46:49], v183 offset:46400
	s_waitcnt lgkmcnt(1)
	v_fmac_f32_e32 v50, v242, v51
	v_and_b32_e32 v51, 0xffff0000, v52
	v_fmac_f32_e32 v50, v243, v51
	v_lshlrev_b32_e32 v51, 16, v53
	v_fmac_f32_e32 v50, v244, v51
	v_and_b32_e32 v51, 0xffff0000, v53
	v_fmac_f32_e32 v50, v245, v51
	v_add_f32_e32 v93, v93, v50
	ds_read_b128 v[50:53], v183 offset:46416
	v_and_b32_e32 v197, 0xffff0000, v198
	v_lshlrev_b32_e32 v95, 16, v198
	s_waitcnt lgkmcnt(1)
	v_mul_f32_e32 v47, v47, v197
	v_fmac_f32_e32 v47, v46, v95
	v_lshlrev_b32_e32 v46, 16, v199
	v_fmac_f32_e32 v47, v48, v46
	v_and_b32_e32 v46, 0xffff0000, v199
	v_fmac_f32_e32 v47, v49, v46
	v_lshlrev_b32_e32 v46, 16, v200
	s_waitcnt lgkmcnt(0)
	v_fmac_f32_e32 v47, v50, v46
	v_and_b32_e32 v46, 0xffff0000, v200
	v_fmac_f32_e32 v47, v51, v46
	v_lshlrev_b32_e32 v46, 16, v201
	v_fmac_f32_e32 v47, v52, v46
	v_and_b32_e32 v46, 0xffff0000, v201
	v_fmac_f32_e32 v47, v53, v46
	v_and_b32_e32 v48, 64, v209
	v_add_f32_e32 v46, v93, v47
	v_xor_b32_e32 v47, 1, v209
	v_add_u32_e32 v48, 64, v48
	v_cmp_lt_i32_e32 vcc, v47, v48
	s_nop 1
	v_cndmask_b32_e32 v47, v209, v47, vcc
	v_lshlrev_b32_e32 v47, 2, v47
	s_nop 1
	v_mov_b32_dpp v47, v46 quad_perm:[1,0,3,2] row_mask:0xf bank_mask:0xf
	s_waitcnt lgkmcnt(0)
	v_add_f32_e32 v46, v46, v47
	v_xor_b32_e32 v47, 2, v209
	v_cmp_lt_i32_e32 vcc, v47, v48
	s_nop 1
	v_cndmask_b32_e32 v47, v209, v47, vcc
	v_lshlrev_b32_e32 v47, 2, v47
	s_nop 1
	v_mov_b32_dpp v47, v46 quad_perm:[2,3,0,1] row_mask:0xf bank_mask:0xf
	s_and_saveexec_b64 s[10:11], s[56:57]
	s_cbranch_execz .LBB0_544
	s_waitcnt lgkmcnt(0)
	v_add_f32_e32 v46, v46, v47
	ds_write_b32 v184, v46 offset:46080

.LBB0_553:
	v_mov_b32_e32 v97, v233
	v_mov_b32_e32 v46, v56
	v_mov_b32_e32 v47, v54
	s_waitcnt lgkmcnt(0)
	v_pk_mul_f32 v[46:47], v[96:97], v[46:47]
	s_nop 0
	v_add_f32_e32 v46, v46, v47
	ds_write_b32 v131, v46 offset:46336
	s_or_b64 exec, exec, s[10:11]
	s_add_i32 s18, s18, -1
	s_cmp_eq_u32 s18, 0
	s_cbranch_scc1 .LBB0_555
